# v54 + attention tail: next-unit table scan via DPP and in-window count via s_bcnt1 (no ds_bpermute chains)
# speedup vs baseline: 1.0083x; 1.0003x over previous
.LBB0_650:
	v_add_f32_e32 v0, v64, v65
	v_add_f32_e32 v0, v66, v0
	v_add_f32_e32 v0, v67, v0
	v_add_f32_e32 v0, v68, v0
	v_add_f32_e32 v0, v69, v0
	v_add_f32_e32 v0, v70, v0
	v_add_f32_e32 v0, v71, v0
	v_add_f32_e32 v0, v72, v0
	v_add_f32_e32 v0, v73, v0
	v_add_f32_e32 v0, v74, v0
	v_add_f32_e32 v0, v75, v0
	v_add_f32_e32 v0, v76, v0
	v_add_f32_e32 v0, v77, v0
	v_add_f32_e32 v0, v78, v0
	v_add_f32_e32 v0, v79, v0
	v_add_f32_e32 v0, v48, v0
	v_add_f32_e32 v0, v49, v0
	v_add_f32_e32 v0, v50, v0
	v_add_f32_e32 v0, v51, v0
	v_add_f32_e32 v0, v52, v0
	v_add_f32_e32 v0, v53, v0
	v_add_f32_e32 v0, v54, v0
	v_add_f32_e32 v0, v55, v0
	v_add_f32_e32 v0, v56, v0
	v_add_f32_e32 v0, v57, v0
	v_add_f32_e32 v0, v58, v0
	v_add_f32_e32 v0, v59, v0
	v_add_f32_e32 v0, v60, v0
	s_lshl_b64 s[16:17], s[10:11], 10
	v_add_f32_e32 v0, v61, v0
	s_cmp_lg_u32 0, -1
	v_add_f32_e32 v0, v62, v0
	s_cselect_b32 s10, 0, 0
	v_add_f32_e32 v0, v63, v0
	s_addk_i32 s10, 0x6000
	v_add_f32_e32 v0, v93, v0
	v_cvt_pk_bf16_f32 v48, v48, v49
	v_add3_u32 v95, v213, s10, v209
	v_cvt_pk_bf16_f32 v64, v64, v65
	v_cvt_pk_bf16_f32 v65, v66, v67
	v_cvt_pk_bf16_f32 v66, v68, v69
	v_cvt_pk_bf16_f32 v67, v70, v71
	v_cvt_pk_bf16_f32 v68, v72, v73
	v_cvt_pk_bf16_f32 v69, v74, v75
	v_cvt_pk_bf16_f32 v70, v76, v77
	v_cvt_pk_bf16_f32 v71, v78, v79
	v_cvt_pk_bf16_f32 v49, v50, v51
	v_cvt_pk_bf16_f32 v50, v52, v53
	v_cvt_pk_bf16_f32 v51, v54, v55
	v_cvt_pk_bf16_f32 v52, v56, v57
	v_cvt_pk_bf16_f32 v53, v58, v59
	v_cvt_pk_bf16_f32 v54, v60, v61
	v_cvt_pk_bf16_f32 v55, v62, v63
	v_add3_u32 v93, v95, v212, s87
	ds_read_b64_tr_b16 v[56:57],v93 offset:0
	ds_read_b64_tr_b16 v[58:59],v93 offset:512
	ds_read_b64_tr_b16 v[60:61],v93 offset:1024
	ds_read_b64_tr_b16 v[62:63],v93 offset:1536
	ds_read_b64_tr_b16 v[72:73],v93 offset:2048
	ds_read_b64_tr_b16 v[74:75],v93 offset:2560
	ds_read_b64_tr_b16 v[76:77],v93 offset:3072
	ds_read_b64_tr_b16 v[78:79],v93 offset:3584
	s_waitcnt lgkmcnt(0)
	s_nop 0
	v_mfma_f32_32x32x16_bf16 v[32:47], v[64:67], v[56:59], v[32:47]
	ds_read_b64_tr_b16 v[56:57],v93 offset:4096
	ds_read_b64_tr_b16 v[58:59],v93 offset:4608
	v_mfma_f32_32x32x16_bf16 v[32:47], v[68:71], v[60:63], v[32:47]
	ds_read_b64_tr_b16 v[60:61],v93 offset:5120
	ds_read_b64_tr_b16 v[62:63],v93 offset:5632
	v_mfma_f32_32x32x16_bf16 v[32:47], v[48:51], v[72:75], v[32:47]
	ds_read_b64_tr_b16 v[72:73],v93 offset:6144
	ds_read_b64_tr_b16 v[74:75],v93 offset:6656
	ds_read_b64_tr_b16 v[96:97],v93 offset:7168
	ds_read_b64_tr_b16 v[98:99],v93 offset:7680
	s_waitcnt lgkmcnt(0)
	v_mfma_f32_32x32x16_bf16 v[32:47], v[52:55], v[76:79], v[32:47]
	v_mfma_f32_32x32x16_bf16 v[16:31], v[64:67], v[56:59], v[16:31]
	v_cmp_gt_u32_e64 s[10:11], 32, v206
	v_mfma_f32_32x32x16_bf16 v[16:31], v[68:71], v[60:63], v[16:31]
	v_mfma_f32_32x32x16_bf16 v[16:31], v[48:51], v[72:75], v[16:31]
	v_mov_b32_e32 v48, v0
	s_nop 1
	v_permlane32_swap_b32_e32 v0, v48
	v_mfma_f32_32x32x16_bf16 v[16:31], v[52:55], v[96:99], v[16:31]
	s_and_saveexec_b64 s[60:61], s[10:11]
	v_add_f32_e32 v0, v0, v48
	ds_write_b32 v214, v0 offset:49280
	s_or_b64 exec, exec, s[60:61]
	s_waitcnt lgkmcnt(0)
	ds_read_b128 v[48:51], v94 offset:49280
	ds_read_b128 v[52:55], v94 offset:49312
	s_lshl_b64 s[16:17], s[16:17], 1
	s_add_u32 s16, s28, s16
	s_addc_u32 s17, s29, s17
	s_waitcnt lgkmcnt(1)
	v_rcp_f32_e32 v0, v48
	v_rcp_f32_e32 v56, v49
	s_add_u32 s12, s16, s12
	s_addc_u32 s13, s17, s13
	s_lshl_b32 s16, s78, 12
	s_add_i32 s16, s16, 0
	v_lshlrev_b32_e32 v63, 1, v207
	v_lshlrev_b32_e32 v64, 9, v208
	v_mul_f32_e32 v32, v32, v0
	v_mul_f32_e32 v0, v16, v0
	v_add3_u32 v63, s16, v63, v64
	v_cvt_pk_bf16_f32 v0, v0, s0
	v_rcp_f32_e32 v57, v50
	v_rcp_f32_e32 v58, v51
	s_waitcnt lgkmcnt(0)
	v_rcp_f32_e32 v59, v52
	ds_read_b128 v[48:51], v94 offset:49344
	v_rcp_f32_e32 v60, v53
	v_rcp_f32_e32 v61, v54
	v_rcp_f32_e32 v62, v55
	ds_read_b128 v[52:55], v94 offset:49376
	ds_write_b16 v63, v0 offset:51264
	v_mul_f32_e32 v0, v33, v56
	v_cvt_pk_bf16_f32 v0, v0, s0
	ds_write_b16 v63, v0 offset:51328
	v_mul_f32_e32 v0, v17, v56
	v_cvt_pk_bf16_f32 v0, v0, s0
	ds_write_b16 v63, v0 offset:51392
	v_mul_f32_e32 v0, v34, v57
	v_cvt_pk_bf16_f32 v0, v0, s0
	ds_write_b16 v63, v0 offset:51456
	v_mul_f32_e32 v0, v18, v57
	v_cvt_pk_bf16_f32 v0, v0, s0
	ds_write_b16 v63, v0 offset:51520
	v_mul_f32_e32 v0, v35, v58
	v_cvt_pk_bf16_f32 v0, v0, s0
	ds_write_b16 v63, v0 offset:51584
	v_mul_f32_e32 v0, v19, v58
	v_cvt_pk_bf16_f32 v0, v0, s0
	ds_write_b16 v63, v0 offset:51648
	v_mul_f32_e32 v0, v36, v59
	v_cvt_pk_bf16_f32 v0, v0, s0
	ds_write_b16 v63, v0 offset:52224
	v_mul_f32_e32 v0, v20, v59
	v_cvt_pk_bf16_f32 v0, v0, s0
	ds_write_b16 v63, v0 offset:52288
	v_mul_f32_e32 v0, v37, v60
	v_cvt_pk_bf16_f32 v0, v0, s0
	ds_write_b16 v63, v0 offset:52352
	v_mul_f32_e32 v0, v21, v60
	v_cvt_pk_bf16_f32 v0, v0, s0
	ds_write_b16 v63, v0 offset:52416
	v_mul_f32_e32 v0, v38, v61
	v_cvt_pk_bf16_f32 v0, v0, s0
	ds_write_b16 v63, v0 offset:52480
	v_mul_f32_e32 v0, v22, v61
	v_cvt_pk_bf16_f32 v0, v0, s0
	s_waitcnt lgkmcnt(13)
	v_rcp_f32_e32 v48, v48
	ds_write_b16 v63, v0 offset:52544
	v_mul_f32_e32 v0, v39, v62
	v_cvt_pk_bf16_f32 v0, v0, s0
	ds_write_b16 v63, v0 offset:52608
	v_mul_f32_e32 v0, v23, v62
	v_cvt_pk_bf16_f32 v0, v0, s0
	v_rcp_f32_e32 v49, v49
	ds_write_b16 v63, v0 offset:52672
	v_mul_f32_e32 v0, v40, v48
	v_cvt_pk_bf16_f32 v0, v0, s0
	ds_write_b16 v63, v0 offset:53248
	v_mul_f32_e32 v0, v24, v48
	v_cvt_pk_bf16_f32 v0, v0, s0
	v_rcp_f32_e32 v50, v50
	ds_write_b16 v63, v0 offset:53312
	v_mul_f32_e32 v0, v41, v49
	v_cvt_pk_bf16_f32 v0, v0, s0
	ds_write_b16 v63, v0 offset:53376
	v_mul_f32_e32 v0, v25, v49
	v_cvt_pk_bf16_f32 v0, v0, s0
	v_rcp_f32_e32 v51, v51
	ds_write_b16 v63, v0 offset:53440
	v_mul_f32_e32 v0, v42, v50
	v_cvt_pk_bf16_f32 v0, v0, s0
	ds_write_b16 v63, v0 offset:53504
	v_mul_f32_e32 v0, v26, v50
	v_cvt_pk_bf16_f32 v0, v0, s0
	s_waitcnt lgkmcnt(14)
	v_rcp_f32_e32 v52, v52
	ds_write_b16 v63, v0 offset:53568
	v_mul_f32_e32 v0, v43, v51
	v_cvt_pk_bf16_f32 v0, v0, s0
	ds_write_b16 v63, v0 offset:53632
	v_mul_f32_e32 v0, v27, v51
	v_cvt_pk_bf16_f32 v0, v0, s0
	v_rcp_f32_e32 v53, v53
	ds_write_b16 v63, v0 offset:53696
	v_mul_f32_e32 v0, v44, v52
	v_cvt_pk_bf16_f32 v0, v0, s0
	ds_write_b16 v63, v0 offset:54272
	v_mul_f32_e32 v0, v28, v52
	v_cvt_pk_bf16_f32 v0, v0, s0
	v_rcp_f32_e32 v54, v54
	ds_write_b16 v63, v0 offset:54336
	v_mul_f32_e32 v0, v45, v53
	v_cvt_pk_bf16_f32 v0, v0, s0
	ds_write_b16 v63, v0 offset:54400
	v_mul_f32_e32 v0, v29, v53
	v_cvt_pk_bf16_f32 v0, v0, s0
	v_rcp_f32_e32 v55, v55
	ds_write_b16 v63, v0 offset:54464
	v_mul_f32_e32 v0, v46, v54
	v_cvt_pk_bf16_f32 v0, v0, s0
	ds_write_b16 v63, v0 offset:54528
	v_mul_f32_e32 v0, v30, v54
	v_cvt_pk_bf16_f32 v0, v0, s0
	ds_write_b16 v63, v0 offset:54592
	v_mul_f32_e32 v0, v47, v55
	v_cvt_pk_bf16_f32 v0, v0, s0
	ds_write_b16 v63, v0 offset:54656
	v_mul_f32_e32 v0, v31, v55
	v_cvt_pk_bf16_f32 v32, v32, s0
	v_cvt_pk_bf16_f32 v0, v0, s0
	ds_write_b16 v63, v32 offset:51200
	ds_write_b16 v63, v0 offset:54720
	v_lshlrev_b32_e32 v0, 7, v14
	v_lshlrev_b32_e32 v14, 1, v90
	s_waitcnt lgkmcnt(0)
	v_add3_u32 v0, s16, v0, v14
	ds_read_b128 v[16:19], v0 offset:51200
	ds_read_b128 v[20:23], v0 offset:52224
	s_waitcnt vmcnt(3)
	v_lshlrev_b32_e32 v28, 16, v80
	v_and_b32_e32 v29, 0xffff0000, v80
	v_lshl_add_u64 v[24:25], v[88:89], 1, s[12:13]
	s_waitcnt lgkmcnt(1)
	v_lshlrev_b32_e32 v26, 16, v16
	v_and_b32_e32 v27, 0xffff0000, v16
	v_pk_mul_f32 v[26:27], v[28:29], v[26:27]
	v_lshlrev_b32_e32 v28, 16, v81
	v_cvt_pk_bf16_f32 v16, v26, v27
	v_lshlrev_b32_e32 v26, 16, v17
	v_and_b32_e32 v27, 0xffff0000, v17
	v_and_b32_e32 v29, 0xffff0000, v81
	v_pk_mul_f32 v[26:27], v[28:29], v[26:27]
	v_lshlrev_b32_e32 v28, 16, v82
	v_cvt_pk_bf16_f32 v17, v26, v27
	v_lshlrev_b32_e32 v26, 16, v18
	v_and_b32_e32 v27, 0xffff0000, v18
	v_and_b32_e32 v29, 0xffff0000, v82
	v_pk_mul_f32 v[26:27], v[28:29], v[26:27]
	v_lshlrev_b32_e32 v28, 16, v83
	v_cvt_pk_bf16_f32 v18, v26, v27
	v_lshlrev_b32_e32 v26, 16, v19
	v_and_b32_e32 v27, 0xffff0000, v19
	v_and_b32_e32 v29, 0xffff0000, v83
	v_pk_mul_f32 v[26:27], v[28:29], v[26:27]
	s_nop 0
	v_cvt_pk_bf16_f32 v19, v26, v27
	global_store_dwordx4 v[24:25], v[16:19], off sc1
	s_waitcnt lgkmcnt(0)
	s_nop 0
	v_lshlrev_b32_e32 v16, 16, v20
	v_and_b32_e32 v17, 0xffff0000, v20
	s_waitcnt vmcnt(3)
	v_lshlrev_b32_e32 v18, 16, v10
	v_and_b32_e32 v19, 0xffff0000, v10
	v_pk_mul_f32 v[16:17], v[18:19], v[16:17]
	v_lshlrev_b32_e32 v18, 16, v11
	v_cvt_pk_bf16_f32 v10, v16, v17
	v_lshlrev_b32_e32 v16, 16, v21
	v_and_b32_e32 v17, 0xffff0000, v21
	v_and_b32_e32 v19, 0xffff0000, v11
	v_pk_mul_f32 v[16:17], v[18:19], v[16:17]
	v_lshlrev_b32_e32 v18, 16, v12
	v_cvt_pk_bf16_f32 v11, v16, v17
	v_lshlrev_b32_e32 v16, 16, v22
	v_and_b32_e32 v17, 0xffff0000, v22
	v_and_b32_e32 v19, 0xffff0000, v12
	v_pk_mul_f32 v[16:17], v[18:19], v[16:17]
	v_lshlrev_b32_e32 v18, 16, v13
	v_cvt_pk_bf16_f32 v12, v16, v17
	v_lshlrev_b32_e32 v16, 16, v23
	v_and_b32_e32 v17, 0xffff0000, v23
	v_and_b32_e32 v19, 0xffff0000, v13
	v_pk_mul_f32 v[16:17], v[18:19], v[16:17]
	v_add_co_u32_e32 v20, vcc, s68, v24
	v_cvt_pk_bf16_f32 v13, v16, v17
	ds_read_b128 v[16:19], v0 offset:53248
	v_addc_co_u32_e32 v21, vcc, 0, v25, vcc
	global_store_dwordx4 v[20:21], v[10:13], off sc1
	ds_read_b128 v[10:13], v0 offset:54272
	s_waitcnt lgkmcnt(1)
	v_lshlrev_b32_e32 v20, 16, v16
	v_and_b32_e32 v21, 0xffff0000, v16
	s_waitcnt vmcnt(3)
	v_lshlrev_b32_e32 v22, 16, v6
	v_and_b32_e32 v23, 0xffff0000, v6
	v_pk_mul_f32 v[20:21], v[22:23], v[20:21]
	v_lshlrev_b32_e32 v16, 16, v17
	v_cvt_pk_bf16_f32 v6, v20, v21
	v_and_b32_e32 v17, 0xffff0000, v17
	v_lshlrev_b32_e32 v20, 16, v7
	v_and_b32_e32 v21, 0xffff0000, v7
	v_pk_mul_f32 v[16:17], v[20:21], v[16:17]
	v_lshlrev_b32_e32 v20, 16, v8
	v_cvt_pk_bf16_f32 v7, v16, v17
	v_lshlrev_b32_e32 v16, 16, v18
	v_and_b32_e32 v17, 0xffff0000, v18
	v_and_b32_e32 v21, 0xffff0000, v8
	v_pk_mul_f32 v[16:17], v[20:21], v[16:17]
	v_lshlrev_b32_e32 v18, 16, v9
	v_cvt_pk_bf16_f32 v8, v16, v17
	v_lshlrev_b32_e32 v16, 16, v19
	v_and_b32_e32 v17, 0xffff0000, v19
	v_and_b32_e32 v19, 0xffff0000, v9
	v_pk_mul_f32 v[16:17], v[18:19], v[16:17]
	s_nop 0
	v_cvt_pk_bf16_f32 v9, v16, v17
	v_add_co_u32_e32 v16, vcc, s70, v24
	s_nop 1
	v_addc_co_u32_e32 v17, vcc, 0, v25, vcc
	global_store_dwordx4 v[16:17], v[6:9], off sc1
	s_waitcnt lgkmcnt(0)
	s_nop 0
	v_lshlrev_b32_e32 v6, 16, v10
	v_and_b32_e32 v7, 0xffff0000, v10
	s_waitcnt vmcnt(3)
	v_lshlrev_b32_e32 v8, 16, v2
	v_and_b32_e32 v9, 0xffff0000, v2
	v_pk_mul_f32 v[6:7], v[8:9], v[6:7]
	v_lshlrev_b32_e32 v8, 16, v3
	v_cvt_pk_bf16_f32 v2, v6, v7
	v_lshlrev_b32_e32 v6, 16, v11
	v_and_b32_e32 v7, 0xffff0000, v11
	v_and_b32_e32 v9, 0xffff0000, v3
	v_pk_mul_f32 v[6:7], v[8:9], v[6:7]
	v_lshlrev_b32_e32 v8, 16, v4
	v_cvt_pk_bf16_f32 v3, v6, v7
	v_lshlrev_b32_e32 v6, 16, v12
	v_and_b32_e32 v7, 0xffff0000, v12
	v_and_b32_e32 v9, 0xffff0000, v4
	v_pk_mul_f32 v[6:7], v[8:9], v[6:7]
	v_lshlrev_b32_e32 v8, 16, v5
	v_cvt_pk_bf16_f32 v4, v6, v7
	v_lshlrev_b32_e32 v6, 16, v13
	v_and_b32_e32 v7, 0xffff0000, v13
	v_and_b32_e32 v9, 0xffff0000, v5
	v_pk_mul_f32 v[6:7], v[8:9], v[6:7]
	s_nop 0
	v_cvt_pk_bf16_f32 v5, v6, v7
	v_add_co_u32_e32 v6, vcc, 0xc000, v24
	s_nop 1
	v_addc_co_u32_e32 v7, vcc, 0, v25, vcc
	s_and_b64 vcc, exec, s[0:1]
	global_store_dwordx4 v[6:7], v[2:5], off sc1
	s_cbranch_vccnz .LBB0_544
	s_xor_b32 s20, s77, 1
	s_cmpk_gt_i32 s14, 0x3ff
	s_mov_b64 s[0:1], -1
	s_cbranch_scc1 .LBB0_661
	v_add_f32_e32 v0, v87, v15
	v_add_f32_e32 v2, v0, v92
	v_add_f32_e32 v6, v2, v91
	v_lshlrev_b32_e32 v5, 2, v206
	v_mov_b32_e32 v3, v6
	s_nop 1
	v_add_f32_dpp v3, v3, v3 row_shr:1 row_mask:0xf bank_mask:0xf
	s_nop 1
	v_add_f32_dpp v3, v3, v3 row_shr:2 row_mask:0xf bank_mask:0xf
	s_nop 1
	v_add_f32_dpp v3, v3, v3 row_shr:4 row_mask:0xf bank_mask:0xf
	s_nop 1
	v_add_f32_dpp v3, v3, v3 row_shr:8 row_mask:0xf bank_mask:0xf
	s_nop 1
	v_add_f32_dpp v3, v3, v3 row_bcast:15 row_mask:0xa bank_mask:0xf
	s_nop 1
	v_add_f32_dpp v3, v3, v3 row_bcast:31 row_mask:0xc bank_mask:0xf
	s_nop 0
	v_sub_f32_e32 v8, v3, v6
	v_xad_u32 v4, v5, -1, s15
	v_add_f32_e32 v5, v87, v8
	v_add_f32_e32 v3, v0, v8
	v_add_f32_e32 v0, v6, v8
	v_sub_f32_e32 v6, v5, v87
	v_cmp_ge_f32_e64 s[0:1], v6, -v197
	v_sub_f32_e32 v6, v3, v15
	v_add_f32_e32 v2, v2, v8
	v_cmp_lt_i32_e64 s[10:11], 0, v4
	v_cmp_ge_f32_e64 s[16:17], v6, -v197
	v_cmp_lt_i32_e64 s[12:13], -1, v4
	s_and_b64 s[16:17], s[10:11], s[16:17]
	s_bcnt1_i32_b64 s60, s[16:17]
	v_sub_f32_e32 v8, v2, v92
	s_and_b64 vcc, s[12:13], s[0:1]
	s_bcnt1_i32_b64 s61, vcc
	s_add_i32 s60, s60, s61
	v_cmp_lt_i32_e64 s[0:1], 1, v4
	v_cmp_ge_f32_e64 s[16:17], v8, -v197
	s_and_b64 s[16:17], s[0:1], s[16:17]
	s_bcnt1_i32_b64 s61, s[16:17]
	s_add_i32 s60, s60, s61
	v_sub_f32_e32 v9, v0, v91
	v_cmp_lt_i32_e32 vcc, 2, v4
	v_cmp_ge_f32_e64 s[16:17], v9, -v197
	s_and_b64 s[16:17], vcc, s[16:17]
	s_bcnt1_i32_b64 s61, s[16:17]
	s_add_i32 s60, s60, s61
	s_lshl_b32 s16, s20, 10
	s_add_i32 s56, s16, 0
	s_add_i32 s56, s56, 0x24800
	s_and_saveexec_b64 s[16:17], s[12:13]
	s_cbranch_execnz .LBB0_664
	s_or_b64 exec, exec, s[16:17]
	v_lshlrev_b32_e32 v4, 2, v4
	s_and_saveexec_b64 s[12:13], s[10:11]
	s_cbranch_execnz .LBB0_665

.LBB0_659:
	s_lshl_b32 s12, s15, 2
	s_add_i32 s12, s56, s12
	v_add_f32_e32 v2, v84, v85
	v_mov_b32_e32 v0, s12
	v_add_f32_e32 v3, v2, v86
	s_lshl_b32 s12, s20, 2
	ds_write2_b32 v0, v1, v84 offset1:1
	ds_write2_b32 v0, v2, v3 offset0:2 offset1:3
	v_mov_b32_e32 v0, s60
	s_add_i32 s12, s12, 0
	v_sub_u32_e32 v0, s15, v0
	s_add_i32 s12, s12, 0x26800
	s_mov_b64 s[0:1], exec
	v_and_b32_e32 v0, -2, v0
	v_mov_b32_e32 v2, s12
	ds_write_b32 v2, v0
